# LN1: gamma/beta preloaded once per wave into registers (per-quarter loads and their waits removed) + next-token row prefetch ahead of the stores
# speedup vs baseline: 1.0058x; 1.0058x over previous
.LBB0_593:
	s_cmp_lt_i32 s74, 8
	s_cselect_b64 s[0:1], -1, 0
	s_cmp_gt_i32 s75, 7
	s_cselect_b64 s[4:5], -1, 0
	s_and_b64 s[0:1], s[0:1], s[4:5]
	s_andn2_b64 vcc, exec, s[0:1]
	s_cbranch_vccnz .LBB0_680
	s_load_dwordx2 s[0:1], s[68:69], 56
	s_waitcnt lgkmcnt(0)
	s_lshl_b32 s3, s90, 3
	s_load_dwordx2 s[8:9], s[68:69], 64
	s_waitcnt lgkmcnt(0)
	s_add_i32 s4, s3, s91
	s_cmpk_gt_i32 s4, 0x3fff
	s_cbranch_scc1 .LBB0_597
	v_lshlrev_b32_e32 v1, 3, v0
	v_and_b32_e32 v6, 0x1f8, v1
	v_mbcnt_lo_u32_b32 v1, -1, 0
	v_mbcnt_hi_u32_b32 v2, -1, v1
	v_and_b32_e32 v1, 64, v2
	v_add_u32_e32 v3, 64, v1
	v_xor_b32_e32 v1, 1, v2
	v_cmp_lt_i32_e32 vcc, v1, v3
	v_xor_b32_e32 v4, 2, v2
	s_ashr_i32 s5, s4, 31
	v_cndmask_b32_e32 v1, v2, v1, vcc
	v_cmp_lt_i32_e32 vcc, v4, v3
	s_lshl_b32 s6, s18, 3
	s_ashr_i32 s7, s6, 31
	v_cndmask_b32_e32 v4, v2, v4, vcc
	v_lshlrev_b32_e32 v47, 2, v4
	v_xor_b32_e32 v4, 4, v2
	v_cmp_lt_i32_e32 vcc, v4, v3
	v_lshlrev_b32_e32 v1, 2, v1
	s_lshl_b64 s[10:11], s[6:7], 12
	v_cndmask_b32_e32 v4, v2, v4, vcc
	v_lshlrev_b32_e32 v48, 2, v4
	v_xor_b32_e32 v4, 8, v2
	v_cmp_lt_i32_e32 vcc, v4, v3
	v_mov_b32_e32 v52, 0x3727c5ac
	s_mov_b32 s3, 0xf800000
	v_cndmask_b32_e32 v4, v2, v4, vcc
	v_lshlrev_b32_e32 v49, 2, v4
	v_xor_b32_e32 v4, 16, v2
	v_cmp_lt_i32_e32 vcc, v4, v3
	v_mov_b32_e32 v53, 0x260
	s_mov_b32 s12, 0xc3e00000
	v_cndmask_b32_e32 v4, v2, v4, vcc
	v_lshlrev_b32_e32 v50, 2, v4
	v_xor_b32_e32 v4, 32, v2
	v_cmp_lt_i32_e32 vcc, v4, v3
	v_mov_b32_e32 v3, 0
	v_mov_b32_e32 v5, v3
	v_cndmask_b32_e32 v2, v2, v4, vcc
	v_lshlrev_b32_e32 v51, 2, v2
	v_lshlrev_b32_e32 v2, 2, v6
	v_lshl_add_u64 v[18:19], s[0:1], 0, v[2:3]
	v_lshl_add_u64 v[20:21], s[8:9], 0, v[2:3]
	v_or_b32_e32 v4, 0x1000, v2
	v_or_b32_e32 v2, 0x1800, v2
	v_lshl_add_u64 v[22:23], s[0:1], 0, v[4:5]
	v_lshl_add_u64 v[26:27], s[0:1], 0, v[2:3]
	s_lshl_b64 s[0:1], s[4:5], 11
	v_lshl_add_u64 v[28:29], s[8:9], 0, v[2:3]
	v_or_b32_e32 v30, s0, v6
	v_mov_b32_e32 v31, s1
	s_lshl_b64 s[0:1], s[4:5], 12
	v_and_b32_e32 v2, 63, v0
	v_lshl_add_u64 v[24:25], s[8:9], 0, v[4:5]
	s_lshl_b64 s[8:9], s[6:7], 11
	v_lshl_or_b32 v32, v2, 4, s0
	v_mov_b32_e32 v33, s1
	s_movk_i32 s5, 0x7fff
	s_mov_b32 s7, 0x16b00000
	v_mov_b32_e32 v54, 0x43e00000
	s_mov_b32 s13, 0x12b00000
	v_mov_b32_e32 v55, 1
	global_load_dwordx4 v[120:123], v[18:19], off offset:16
	global_load_dwordx4 v[124:127], v[18:19], off
	global_load_dwordx4 v[128:131], v[20:21], off offset:16
	global_load_dwordx4 v[132:135], v[20:21], off
	global_load_dwordx4 v[136:139], v[18:19], off offset:2048
	global_load_dwordx4 v[140:143], v[20:21], off offset:2048
	global_load_dwordx4 v[144:147], v[18:19], off offset:2064
	global_load_dwordx4 v[148:151], v[20:21], off offset:2064
	global_load_dwordx4 v[152:155], v[22:23], off
	global_load_dwordx4 v[156:159], v[24:25], off
	global_load_dwordx4 v[160:163], v[22:23], off offset:16
	global_load_dwordx4 v[164:167], v[24:25], off offset:16
	global_load_dwordx4 v[168:171], v[26:27], off
	global_load_dwordx4 v[172:175], v[28:29], off
	global_load_dwordx4 v[176:179], v[26:27], off offset:16
	global_load_dwordx4 v[180:183], v[28:29], off offset:16
	s_add_u32 s14, s72, 0xeb00000
	s_addc_u32 s15, s73, 0
	v_lshl_add_u64 v[202:203], s[14:15], 0, v[32:33]
	global_load_dwordx4 v[184:187], v[202:203], off
	global_load_dwordx4 v[188:191], v[202:203], off offset:1024
	global_load_dwordx4 v[192:195], v[202:203], off offset:2048
	global_load_dwordx4 v[198:201], v[202:203], off offset:3072
	s_waitcnt vmcnt(0)
.LBB0_596:
	v_lshl_add_u64 v[38:39], s[72:73], 0, v[32:33]
	v_add_co_u32_e32 v72, vcc, 0xeb00000, v38
	v_add_co_u32_e64 v34, s[0:1], s7, v38
	s_nop 0
	v_addc_co_u32_e32 v73, vcc, 0, v39, vcc
	v_addc_co_u32_e64 v35, s[0:1], 0, v39, s[0:1]
	v_lshl_add_u64 v[36:37], s[72:73], 0, v[30:31]
	v_add_co_u32_e64 v36, s[0:1], s13, v36
	v_mov_b32_e32 v40, 0
	s_nop 0
	v_addc_co_u32_e64 v37, s[0:1], 0, v37, s[0:1]
	v_mov_b32_e32 v41, 0
	v_mov_b32_e32 v42, 0
	v_mov_b32_e32 v43, 0
	v_mov_b32_e32 v44, 0
	v_mov_b32_e32 v45, 0
	s_add_i32 s4, s4, s6
	v_lshl_add_u64 v[30:31], v[30:31], 0, s[8:9]
	v_lshl_add_u64 v[32:33], v[32:33], 0, s[10:11]
	s_cmpk_lt_i32 s4, 0x4000
	v_mov_b32_e32 v56, v184
	v_mov_b32_e32 v57, v185
	v_mov_b32_e32 v58, v186
	v_mov_b32_e32 v59, v187
	v_mov_b32_e32 v60, v188
	v_mov_b32_e32 v61, v189
	v_mov_b32_e32 v62, v190
	v_mov_b32_e32 v63, v191
	v_mov_b32_e32 v64, v192
	v_mov_b32_e32 v65, v193
	v_mov_b32_e32 v66, v194
	v_mov_b32_e32 v67, v195
	v_mov_b32_e32 v68, v198
	v_mov_b32_e32 v69, v199
	v_mov_b32_e32 v70, v200
	v_mov_b32_e32 v71, v201
	v_lshl_add_u64 v[202:203], s[14:15], 0, v[32:33]
	global_load_dwordx4 v[184:187], v[202:203], off
	global_load_dwordx4 v[188:191], v[202:203], off offset:1024
	global_load_dwordx4 v[192:195], v[202:203], off offset:2048
	global_load_dwordx4 v[198:201], v[202:203], off offset:3072
	s_nop 1
	v_mov_b32_e32 v2, v120
	v_mov_b32_e32 v3, v121
	v_mov_b32_e32 v4, v122
	v_mov_b32_e32 v5, v123
	v_mov_b32_e32 v6, v124
	v_mov_b32_e32 v7, v125
	v_mov_b32_e32 v8, v126
	v_mov_b32_e32 v9, v127
	v_mov_b32_e32 v10, v128
	v_mov_b32_e32 v11, v129
	v_mov_b32_e32 v12, v130
	v_mov_b32_e32 v13, v131
	v_mov_b32_e32 v14, v132
	v_mov_b32_e32 v15, v133
	v_mov_b32_e32 v16, v134
	v_mov_b32_e32 v17, v135
	v_mov_b32_e32 v76, v3
	v_mov_b32_e32 v3, v5
	v_mov_b32_e32 v79, v12
	v_mov_b32_e32 v75, v16
	v_mov_b32_e32 v74, v15
	v_mov_b32_e32 v15, v17
	v_mov_b32_e32 v78, v11
	v_lshlrev_b32_e32 v12, 16, v56
	v_and_b32_e32 v16, 0xffff0000, v56
	v_add_f32_e32 v5, 0, v12
	v_lshlrev_b32_e32 v17, 16, v57
	v_add_f32_e32 v5, v5, v16
	v_mov_b32_e32 v11, v13
	v_and_b32_e32 v13, 0xffff0000, v57
	v_add_f32_e32 v5, v5, v17
	v_lshlrev_b32_e32 v38, 16, v58
	v_add_f32_e32 v5, v5, v13
	v_and_b32_e32 v56, 0xffff0000, v58
	v_add_f32_e32 v5, v5, v38
	v_lshlrev_b32_e32 v57, 16, v59
	v_add_f32_e32 v5, v5, v56
	v_and_b32_e32 v39, 0xffff0000, v59
	v_add_f32_e32 v5, v5, v57
	v_lshlrev_b32_e32 v58, 16, v60
	v_add_f32_e32 v5, v5, v39
	v_and_b32_e32 v80, 0xffff0000, v60
	v_add_f32_e32 v5, v5, v58
	v_lshlrev_b32_e32 v81, 16, v61
	v_add_f32_e32 v5, v5, v80
	v_and_b32_e32 v59, 0xffff0000, v61
	v_add_f32_e32 v5, v5, v81
	v_lshlrev_b32_e32 v60, 16, v62
	v_add_f32_e32 v5, v5, v59
	v_and_b32_e32 v82, 0xffff0000, v62
	v_add_f32_e32 v5, v5, v60
	v_lshlrev_b32_e32 v83, 16, v63
	v_add_f32_e32 v5, v5, v82
	v_and_b32_e32 v61, 0xffff0000, v63
	v_add_f32_e32 v5, v5, v83
	v_lshlrev_b32_e32 v62, 16, v64
	v_add_f32_e32 v5, v5, v61
	v_and_b32_e32 v84, 0xffff0000, v64
	v_add_f32_e32 v5, v5, v62
	v_lshlrev_b32_e32 v85, 16, v65
	v_add_f32_e32 v5, v5, v84
	v_and_b32_e32 v63, 0xffff0000, v65
	v_add_f32_e32 v5, v5, v85
	v_lshlrev_b32_e32 v64, 16, v66
	v_add_f32_e32 v5, v5, v63
	v_and_b32_e32 v86, 0xffff0000, v66
	v_add_f32_e32 v5, v5, v64
	v_lshlrev_b32_e32 v87, 16, v67
	v_add_f32_e32 v5, v5, v86
	v_and_b32_e32 v65, 0xffff0000, v67
	v_add_f32_e32 v5, v5, v87
	v_lshlrev_b32_e32 v66, 16, v68
	v_add_f32_e32 v5, v5, v65
	v_and_b32_e32 v88, 0xffff0000, v68
	v_add_f32_e32 v5, v5, v66
	v_lshlrev_b32_e32 v89, 16, v69
	v_add_f32_e32 v5, v5, v88
	v_and_b32_e32 v67, 0xffff0000, v69
	v_add_f32_e32 v5, v5, v89
	v_mov_b32_e32 v77, v4
	v_lshlrev_b32_e32 v4, 16, v70
	v_add_f32_e32 v5, v5, v67
	v_mov_b32_e32 v73, v8
	v_and_b32_e32 v8, 0xffff0000, v70
	v_add_f32_e32 v5, v5, v4
	v_lshlrev_b32_e32 v69, 16, v71
	v_add_f32_e32 v5, v5, v8
	v_and_b32_e32 v68, 0xffff0000, v71
	v_add_f32_e32 v5, v5, v69
	v_add_f32_e32 v5, v5, v68
	v_mov_b32_e32 v72, v7
	v_mov_b32_e32 v7, v9
	s_nop 1
	v_mov_b32_dpp v9, v5 quad_perm:[1,0,3,2] row_mask:0xf bank_mask:0xf
	s_waitcnt lgkmcnt(0)
	v_add_f32_e32 v5, v5, v9
	s_nop 1
	v_mov_b32_dpp v9, v5 quad_perm:[2,3,0,1] row_mask:0xf bank_mask:0xf
	s_waitcnt lgkmcnt(0)
	v_add_f32_e32 v5, v5, v9
	s_nop 1
	v_mov_b32_dpp v9, v5 row_half_mirror row_mask:0xf bank_mask:0xf
	s_waitcnt lgkmcnt(0)
	v_add_f32_e32 v5, v5, v9
	s_nop 1
	v_mov_b32_dpp v9, v5 row_mirror row_mask:0xf bank_mask:0xf
	s_waitcnt lgkmcnt(0)
	v_add_f32_e32 v5, v5, v9
	v_mov_b32_e32 v9, v5
	v_mov_b32_e32 v244, v5
	s_nop 1
	v_permlane16_swap_b32 v9, v244
	s_nop 1
	s_waitcnt lgkmcnt(0)
	v_add_f32_e32 v5, v9, v244
	v_mov_b32_e32 v9, v5
	v_mov_b32_e32 v244, v5
	s_nop 1
	v_permlane32_swap_b32 v9, v244
	s_nop 1
	s_waitcnt lgkmcnt(0)
	v_add_f32_e32 v5, v9, v244
	v_mul_f32_e32 v46, 0x3a000000, v5
	v_pk_add_f32 v[70:71], v[12:13], v[46:47] op_sel_hi:[1,0] neg_lo:[0,1] neg_hi:[0,1]
	v_pk_add_f32 v[90:91], v[16:17], v[46:47] op_sel_hi:[1,0] neg_lo:[0,1] neg_hi:[0,1]
	v_pk_add_f32 v[92:93], v[38:39], v[46:47] op_sel_hi:[1,0] neg_lo:[0,1] neg_hi:[0,1]
	v_pk_add_f32 v[12:13], v[66:67], v[46:47] op_sel_hi:[1,0] neg_lo:[0,1] neg_hi:[0,1]
	v_pk_add_f32 v[38:39], v[68:69], v[46:47] op_sel_hi:[1,0] neg_lo:[0,1] neg_hi:[0,1]
	v_pk_mul_f32 v[66:67], v[70:71], v[70:71]
	v_pk_mul_f32 v[68:69], v[90:91], v[90:91]
	v_fmac_f32_e32 v4, 0xba000000, v5
	v_fmac_f32_e32 v8, 0xba000000, v5
	v_add_f32_e32 v5, v66, v68
	v_add_f32_e32 v5, v69, v5
	v_pk_add_f32 v[56:57], v[56:57], v[46:47] op_sel_hi:[1,0] neg_lo:[0,1] neg_hi:[0,1]
	v_pk_add_f32 v[16:17], v[88:89], v[46:47] op_sel_hi:[1,0] neg_lo:[0,1] neg_hi:[0,1]
	v_pk_mul_f32 v[88:89], v[92:93], v[92:93]
	v_add_f32_e32 v5, v67, v5
	v_pk_mul_f32 v[94:95], v[56:57], v[56:57]
	v_add_f32_e32 v5, v88, v5
	v_add_f32_e32 v5, v94, v5
	v_pk_add_f32 v[58:59], v[58:59], v[46:47] op_sel_hi:[1,0] neg_lo:[0,1] neg_hi:[0,1]
	v_add_f32_e32 v5, v95, v5
	v_pk_add_f32 v[80:81], v[80:81], v[46:47] op_sel_hi:[1,0] neg_lo:[0,1] neg_hi:[0,1]
	v_pk_mul_f32 v[96:97], v[58:59], v[58:59]
	v_add_f32_e32 v5, v89, v5
	v_pk_mul_f32 v[98:99], v[80:81], v[80:81]
	v_add_f32_e32 v5, v96, v5
	v_add_f32_e32 v5, v98, v5
	v_pk_add_f32 v[60:61], v[60:61], v[46:47] op_sel_hi:[1,0] neg_lo:[0,1] neg_hi:[0,1]
	v_add_f32_e32 v5, v99, v5
	v_pk_add_f32 v[82:83], v[82:83], v[46:47] op_sel_hi:[1,0] neg_lo:[0,1] neg_hi:[0,1]
	v_pk_mul_f32 v[100:101], v[60:61], v[60:61]
	v_add_f32_e32 v5, v97, v5
	v_pk_mul_f32 v[102:103], v[82:83], v[82:83]
	v_add_f32_e32 v5, v100, v5
	v_add_f32_e32 v5, v102, v5
	v_pk_add_f32 v[62:63], v[62:63], v[46:47] op_sel_hi:[1,0] neg_lo:[0,1] neg_hi:[0,1]
	v_add_f32_e32 v5, v103, v5
	v_pk_add_f32 v[84:85], v[84:85], v[46:47] op_sel_hi:[1,0] neg_lo:[0,1] neg_hi:[0,1]
	v_pk_mul_f32 v[104:105], v[62:63], v[62:63]
	v_add_f32_e32 v5, v101, v5
	v_pk_mul_f32 v[106:107], v[84:85], v[84:85]
	v_add_f32_e32 v5, v104, v5
	v_add_f32_e32 v5, v106, v5
	v_pk_add_f32 v[64:65], v[64:65], v[46:47] op_sel_hi:[1,0] neg_lo:[0,1] neg_hi:[0,1]
	v_add_f32_e32 v5, v107, v5
	v_pk_add_f32 v[86:87], v[86:87], v[46:47] op_sel_hi:[1,0] neg_lo:[0,1] neg_hi:[0,1]
	v_pk_mul_f32 v[108:109], v[64:65], v[64:65]
	v_add_f32_e32 v5, v105, v5
	v_pk_mul_f32 v[110:111], v[86:87], v[86:87]
	v_add_f32_e32 v5, v108, v5
	v_add_f32_e32 v5, v110, v5
	v_add_f32_e32 v5, v111, v5
	v_pk_mul_f32 v[112:113], v[12:13], v[12:13]
	v_add_f32_e32 v5, v109, v5
	v_pk_mul_f32 v[114:115], v[16:17], v[16:17]
	v_add_f32_e32 v5, v112, v5
	v_add_f32_e32 v5, v114, v5
	v_add_f32_e32 v5, v115, v5
	v_add_f32_e32 v5, v113, v5
	v_fmac_f32_e32 v5, v4, v4
	v_pk_mul_f32 v[116:117], v[38:39], v[38:39]
	v_fmac_f32_e32 v5, v8, v8
	v_add_f32_e32 v5, v117, v5
	v_add_f32_e32 v5, v116, v5
	s_nop 1
	v_mov_b32_dpp v9, v5 quad_perm:[1,0,3,2] row_mask:0xf bank_mask:0xf
	s_waitcnt lgkmcnt(0)
	v_add_f32_e32 v5, v5, v9
	s_nop 1
	v_mov_b32_dpp v9, v5 quad_perm:[2,3,0,1] row_mask:0xf bank_mask:0xf
	s_waitcnt lgkmcnt(0)
	v_add_f32_e32 v5, v5, v9
	s_nop 1
	v_mov_b32_dpp v9, v5 row_half_mirror row_mask:0xf bank_mask:0xf
	s_waitcnt lgkmcnt(0)
	v_add_f32_e32 v5, v5, v9
	s_nop 1
	v_mov_b32_dpp v9, v5 row_mirror row_mask:0xf bank_mask:0xf
	s_waitcnt lgkmcnt(0)
	v_add_f32_e32 v5, v5, v9
	v_mov_b32_e32 v9, v5
	v_mov_b32_e32 v244, v5
	s_nop 1
	v_permlane16_swap_b32 v9, v244
	s_nop 1
	s_waitcnt lgkmcnt(0)
	v_add_f32_e32 v5, v9, v244
	v_mov_b32_e32 v9, v5
	v_mov_b32_e32 v244, v5
	s_nop 1
	v_permlane32_swap_b32 v9, v244
	s_nop 1
	s_waitcnt lgkmcnt(0)
	v_add_f32_e32 v5, v9, v244
	v_fmamk_f32 v5, v5, 0x3a000000, v52
	v_mul_f32_e32 v9, 0x4f800000, v5
	v_cmp_gt_f32_e32 vcc, s3, v5
	s_nop 1
	v_cndmask_b32_e32 v5, v5, v9, vcc
	v_sqrt_f32_e32 v9, v5
	s_nop 0
	v_add_u32_e32 v46, -1, v9
	v_add_u32_e32 v66, 1, v9
	v_fma_f32 v67, -v46, v9, v5
	v_fma_f32 v68, -v66, v9, v5
	v_cmp_ge_f32_e64 s[0:1], 0, v67
	s_nop 1
	v_cndmask_b32_e64 v9, v9, v46, s[0:1]
	v_cmp_lt_f32_e64 s[0:1], 0, v68
	s_nop 1
	v_cndmask_b32_e64 v9, v9, v66, s[0:1]
	v_mul_f32_e32 v46, 0x37800000, v9
	v_cndmask_b32_e32 v9, v9, v46, vcc
	v_cmp_class_f32_e32 vcc, v5, v53
	s_nop 1
	v_cndmask_b32_e32 v5, v9, v5, vcc
	v_div_scale_f32 v9, s[0:1], v5, v5, 1.0
	v_rcp_f32_e32 v66, v9
	v_div_scale_f32 v46, vcc, 1.0, v5, 1.0
	v_fma_f32 v67, -v9, v66, 1.0
	v_fmac_f32_e32 v66, v67, v66
	v_mul_f32_e32 v67, v46, v66
	v_fma_f32 v68, -v9, v67, v46
	v_fmac_f32_e32 v67, v68, v66
	v_fma_f32 v9, -v9, v67, v46
	v_div_fmas_f32 v9, v9, v66, v67
	v_div_fixup_f32 v46, v9, v5, 1.0
	v_pk_mul_f32 v[66:67], v[90:91], v[46:47] op_sel_hi:[1,0]
	v_pk_mul_f32 v[68:69], v[70:71], v[46:47] op_sel_hi:[1,0]
	v_pk_mul_f32 v[56:57], v[56:57], v[46:47] op_sel_hi:[1,0]
	v_pk_mul_f32 v[70:71], v[92:93], v[46:47] op_sel_hi:[1,0]
	v_pk_mul_f32 v[88:89], v[58:59], v[46:47] op_sel_hi:[1,0]
	v_pk_fma_f32 v[58:59], v[72:73], v[66:67], v[74:75]
	v_pk_fma_f32 v[6:7], v[6:7], v[68:69], v[14:15]
	v_pk_fma_f32 v[14:15], v[76:77], v[56:57], v[78:79]
	v_pk_fma_f32 v[2:3], v[2:3], v[70:71], v[10:11]
	v_pk_mul_f32 v[90:91], v[60:61], v[46:47] op_sel_hi:[1,0]
	v_and_b32_sdwa v9, v58, v55 dst_sel:DWORD dst_unused:UNUSED_PAD src0_sel:WORD_1 src1_sel:DWORD
	v_and_b32_sdwa v10, v7, v55 dst_sel:DWORD dst_unused:UNUSED_PAD src0_sel:WORD_1 src1_sel:DWORD
	v_and_b32_sdwa v11, v6, v55 dst_sel:DWORD dst_unused:UNUSED_PAD src0_sel:WORD_1 src1_sel:DWORD
	v_and_b32_sdwa v57, v14, v55 dst_sel:DWORD dst_unused:UNUSED_PAD src0_sel:WORD_1 src1_sel:DWORD
	v_and_b32_sdwa v60, v3, v55 dst_sel:DWORD dst_unused:UNUSED_PAD src0_sel:WORD_1 src1_sel:DWORD
	v_and_b32_sdwa v61, v2, v55 dst_sel:DWORD dst_unused:UNUSED_PAD src0_sel:WORD_1 src1_sel:DWORD
	v_and_b32_sdwa v5, v59, v55 dst_sel:DWORD dst_unused:UNUSED_PAD src0_sel:WORD_1 src1_sel:DWORD
	v_and_b32_sdwa v56, v15, v55 dst_sel:DWORD dst_unused:UNUSED_PAD src0_sel:WORD_1 src1_sel:DWORD
	v_add3_u32 v9, v58, v9, s5
	v_add3_u32 v7, v7, v10, s5
	v_add3_u32 v6, v6, v11, s5
	v_add3_u32 v11, v14, v57, s5
	v_add3_u32 v3, v3, v60, s5
	v_add3_u32 v2, v2, v61, s5
	v_add3_u32 v5, v59, v5, s5
	v_add3_u32 v10, v15, v56, s5
	v_and_b32_e32 v9, 0xffff0000, v9
	v_and_b32_e32 v7, 0xffff0000, v7
	v_and_b32_e32 v11, 0xffff0000, v11
	v_and_b32_e32 v3, 0xffff0000, v3
	v_and_b32_e32 v14, 0xffff0000, v6
	v_and_b32_e32 v60, 0xffff0000, v2
	v_and_b32_e32 v15, 0xffff0000, v5
	v_and_b32_e32 v61, 0xffff0000, v10
	v_or_b32_sdwa v57, v7, v5 dst_sel:DWORD dst_unused:UNUSED_PAD src0_sel:DWORD src1_sel:WORD_1
	v_or_b32_sdwa v56, v6, v9 dst_sel:DWORD dst_unused:UNUSED_PAD src0_sel:WORD_1 src1_sel:DWORD
	v_or_b32_sdwa v59, v3, v10 dst_sel:DWORD dst_unused:UNUSED_PAD src0_sel:DWORD src1_sel:WORD_1
	v_or_b32_sdwa v58, v2, v11 dst_sel:DWORD dst_unused:UNUSED_PAD src0_sel:WORD_1 src1_sel:DWORD
	v_mul_f32_e32 v2, 0x42000000, v14
	v_mul_f32_e32 v5, 0x42000000, v9
	v_mul_f32_e32 v9, 0x42000000, v60
	v_mul_f32_e32 v10, 0x42000000, v11
	v_med3_f32 v2, v2, s12, v54
	v_med3_f32 v5, v5, s12, v54
	v_med3_f32 v9, v9, s12, v54
	v_med3_f32 v10, v10, s12, v54
	v_cvt_pk_fp8_f32 v40, v2, v5
	v_cvt_pk_fp8_f32 v41, v9, v10
	v_mul_f32_e32 v6, 0x42000000, v15
	v_mul_f32_e32 v7, 0x42000000, v7
	v_mul_f32_e32 v11, 0x42000000, v61
	v_mul_f32_e32 v3, 0x42000000, v3
	v_med3_f32 v6, v6, s12, v54
	v_med3_f32 v7, v7, s12, v54
	v_med3_f32 v11, v11, s12, v54
	v_med3_f32 v3, v3, s12, v54
	v_cvt_pk_fp8_f32 v40, v6, v7 op_sel:[0,0,1]
	v_cvt_pk_fp8_f32 v41, v11, v3 op_sel:[0,0,1]
	global_store_dwordx4 v[34:35], v[56:59], off
	v_pk_mul_f32 v[92:93], v[62:63], v[46:47] op_sel_hi:[1,0]
	v_pk_mul_f32 v[94:95], v[64:65], v[46:47] op_sel_hi:[1,0]
	global_store_dwordx2 v[36:37], v[40:41], off
	s_nop 1
	v_mov_b32_e32 v56, v136
	v_mov_b32_e32 v57, v137
	v_mov_b32_e32 v58, v138
	v_mov_b32_e32 v59, v139
	v_mov_b32_e32 v60, v140
	v_mov_b32_e32 v61, v141
	v_mov_b32_e32 v62, v142
	v_mov_b32_e32 v63, v143
	v_mov_b32_e32 v64, v144
	v_mov_b32_e32 v65, v145
	v_mov_b32_e32 v66, v146
	v_mov_b32_e32 v67, v147
	v_mov_b32_e32 v68, v148
	v_mov_b32_e32 v69, v149
	v_mov_b32_e32 v70, v150
	v_mov_b32_e32 v71, v151
	v_pk_mul_f32 v[80:81], v[80:81], v[46:47] op_sel_hi:[1,0]
	v_pk_mul_f32 v[82:83], v[82:83], v[46:47] op_sel_hi:[1,0]
	v_pk_mul_f32 v[84:85], v[84:85], v[46:47] op_sel_hi:[1,0]
	v_pk_mul_f32 v[86:87], v[86:87], v[46:47] op_sel_hi:[1,0]
	v_mov_b32_e32 v2, v57
	v_mov_b32_e32 v3, v58
	v_mov_b32_e32 v6, v61
	v_mov_b32_e32 v7, v62
	v_mov_b32_e32 v57, v59
	v_mov_b32_e32 v61, v63
	v_mov_b32_e32 v10, v65
	v_mov_b32_e32 v11, v66
	v_mov_b32_e32 v14, v69
	v_mov_b32_e32 v15, v70
	v_mov_b32_e32 v65, v67
	v_mov_b32_e32 v69, v71
	v_pk_fma_f32 v[2:3], v[2:3], v[80:81], v[6:7]
	v_pk_fma_f32 v[6:7], v[56:57], v[88:89], v[60:61]
	v_pk_fma_f32 v[10:11], v[10:11], v[82:83], v[14:15]
	v_pk_fma_f32 v[14:15], v[64:65], v[90:91], v[68:69]
	v_and_b32_sdwa v5, v3, v55 dst_sel:DWORD dst_unused:UNUSED_PAD src0_sel:WORD_1 src1_sel:DWORD
	v_and_b32_sdwa v9, v2, v55 dst_sel:DWORD dst_unused:UNUSED_PAD src0_sel:WORD_1 src1_sel:DWORD
	v_and_b32_sdwa v40, v7, v55 dst_sel:DWORD dst_unused:UNUSED_PAD src0_sel:WORD_1 src1_sel:DWORD
	v_and_b32_sdwa v41, v6, v55 dst_sel:DWORD dst_unused:UNUSED_PAD src0_sel:WORD_1 src1_sel:DWORD
	v_and_b32_sdwa v56, v11, v55 dst_sel:DWORD dst_unused:UNUSED_PAD src0_sel:WORD_1 src1_sel:DWORD
	v_and_b32_sdwa v57, v10, v55 dst_sel:DWORD dst_unused:UNUSED_PAD src0_sel:WORD_1 src1_sel:DWORD
	v_and_b32_sdwa v58, v15, v55 dst_sel:DWORD dst_unused:UNUSED_PAD src0_sel:WORD_1 src1_sel:DWORD
	v_and_b32_sdwa v59, v14, v55 dst_sel:DWORD dst_unused:UNUSED_PAD src0_sel:WORD_1 src1_sel:DWORD
	v_add3_u32 v3, v3, v5, s5
	v_add3_u32 v2, v2, v9, s5
	v_add3_u32 v5, v7, v40, s5
	v_add3_u32 v6, v6, v41, s5
	v_add3_u32 v7, v11, v56, s5
	v_add3_u32 v9, v10, v57, s5
	v_add3_u32 v10, v15, v58, s5
	v_add3_u32 v11, v14, v59, s5
	v_and_b32_e32 v2, 0xffff0000, v2
	v_and_b32_e32 v5, 0xffff0000, v5
	v_and_b32_e32 v9, 0xffff0000, v9
	v_and_b32_e32 v10, 0xffff0000, v10
	v_and_b32_e32 v14, 0xffff0000, v6
	v_and_b32_e32 v40, 0xffff0000, v11
	v_and_b32_e32 v15, 0xffff0000, v3
	v_and_b32_e32 v41, 0xffff0000, v7
	v_or_b32_sdwa v57, v5, v3 dst_sel:DWORD dst_unused:UNUSED_PAD src0_sel:DWORD src1_sel:WORD_1
	v_or_b32_sdwa v56, v6, v2 dst_sel:DWORD dst_unused:UNUSED_PAD src0_sel:WORD_1 src1_sel:DWORD
	v_or_b32_sdwa v59, v10, v7 dst_sel:DWORD dst_unused:UNUSED_PAD src0_sel:DWORD src1_sel:WORD_1
	v_or_b32_sdwa v58, v11, v9 dst_sel:DWORD dst_unused:UNUSED_PAD src0_sel:WORD_1 src1_sel:DWORD
	v_mul_f32_e32 v3, 0x42000000, v14
	v_mul_f32_e32 v2, 0x42000000, v2
	v_mul_f32_e32 v7, 0x42000000, v40
	v_mul_f32_e32 v9, 0x42000000, v9
	v_med3_f32 v3, v3, s12, v54
	v_med3_f32 v2, v2, s12, v54
	v_med3_f32 v7, v7, s12, v54
	v_med3_f32 v9, v9, s12, v54
	v_cvt_pk_fp8_f32 v42, v3, v2
	v_cvt_pk_fp8_f32 v43, v7, v9
	v_mul_f32_e32 v6, 0x42000000, v15
	v_mul_f32_e32 v5, 0x42000000, v5
	v_mul_f32_e32 v11, 0x42000000, v41
	v_mul_f32_e32 v10, 0x42000000, v10
	v_med3_f32 v6, v6, s12, v54
	v_med3_f32 v5, v5, s12, v54
	v_med3_f32 v11, v11, s12, v54
	v_med3_f32 v10, v10, s12, v54
	v_cvt_pk_fp8_f32 v42, v6, v5 op_sel:[0,0,1]
	v_cvt_pk_fp8_f32 v43, v11, v10 op_sel:[0,0,1]
	global_store_dwordx4 v[34:35], v[56:59], off offset:1024
	global_store_dwordx2 v[36:37], v[42:43], off offset:512
	s_nop 1
	v_mov_b32_e32 v40, v152
	v_mov_b32_e32 v41, v153
	v_mov_b32_e32 v42, v154
	v_mov_b32_e32 v43, v155
	s_nop 0
	v_mov_b32_e32 v56, v156
	v_mov_b32_e32 v57, v157
	v_mov_b32_e32 v58, v158
	v_mov_b32_e32 v59, v159
	v_mov_b32_e32 v60, v160
	v_mov_b32_e32 v61, v161
	v_mov_b32_e32 v62, v162
	v_mov_b32_e32 v63, v163
	v_mov_b32_e32 v64, v164
	v_mov_b32_e32 v65, v165
	v_mov_b32_e32 v66, v166
	v_mov_b32_e32 v67, v167
	v_mov_b32_e32 v2, v41
	v_mov_b32_e32 v3, v42
	v_mov_b32_e32 v6, v57
	v_mov_b32_e32 v7, v58
	v_mov_b32_e32 v41, v43
	v_mov_b32_e32 v57, v59
	v_mov_b32_e32 v10, v61
	v_mov_b32_e32 v11, v62
	v_mov_b32_e32 v14, v65
	v_mov_b32_e32 v15, v66
	v_mov_b32_e32 v61, v63
	v_mov_b32_e32 v65, v67
	v_pk_fma_f32 v[2:3], v[2:3], v[84:85], v[6:7]
	v_pk_fma_f32 v[6:7], v[40:41], v[92:93], v[56:57]
	v_pk_fma_f32 v[10:11], v[10:11], v[86:87], v[14:15]
	v_pk_fma_f32 v[14:15], v[60:61], v[94:95], v[64:65]
	v_and_b32_sdwa v5, v3, v55 dst_sel:DWORD dst_unused:UNUSED_PAD src0_sel:WORD_1 src1_sel:DWORD
	v_and_b32_sdwa v9, v2, v55 dst_sel:DWORD dst_unused:UNUSED_PAD src0_sel:WORD_1 src1_sel:DWORD
	v_and_b32_sdwa v40, v7, v55 dst_sel:DWORD dst_unused:UNUSED_PAD src0_sel:WORD_1 src1_sel:DWORD
	v_and_b32_sdwa v41, v6, v55 dst_sel:DWORD dst_unused:UNUSED_PAD src0_sel:WORD_1 src1_sel:DWORD
	v_and_b32_sdwa v42, v11, v55 dst_sel:DWORD dst_unused:UNUSED_PAD src0_sel:WORD_1 src1_sel:DWORD
	v_and_b32_sdwa v43, v10, v55 dst_sel:DWORD dst_unused:UNUSED_PAD src0_sel:WORD_1 src1_sel:DWORD
	v_and_b32_sdwa v56, v15, v55 dst_sel:DWORD dst_unused:UNUSED_PAD src0_sel:WORD_1 src1_sel:DWORD
	v_and_b32_sdwa v57, v14, v55 dst_sel:DWORD dst_unused:UNUSED_PAD src0_sel:WORD_1 src1_sel:DWORD
	v_add3_u32 v3, v3, v5, s5
	v_add3_u32 v2, v2, v9, s5
	v_add3_u32 v5, v7, v40, s5
	v_add3_u32 v6, v6, v41, s5
	v_add3_u32 v7, v11, v42, s5
	v_add3_u32 v9, v10, v43, s5
	v_add3_u32 v10, v15, v56, s5
	v_add3_u32 v11, v14, v57, s5
	v_and_b32_e32 v2, 0xffff0000, v2
	v_and_b32_e32 v5, 0xffff0000, v5
	v_and_b32_e32 v9, 0xffff0000, v9
	v_and_b32_e32 v10, 0xffff0000, v10
	v_and_b32_e32 v14, 0xffff0000, v6
	v_and_b32_e32 v56, 0xffff0000, v11
	v_and_b32_e32 v15, 0xffff0000, v3
	v_and_b32_e32 v57, 0xffff0000, v7
	v_or_b32_sdwa v41, v5, v3 dst_sel:DWORD dst_unused:UNUSED_PAD src0_sel:DWORD src1_sel:WORD_1
	v_or_b32_sdwa v40, v6, v2 dst_sel:DWORD dst_unused:UNUSED_PAD src0_sel:WORD_1 src1_sel:DWORD
	v_or_b32_sdwa v43, v10, v7 dst_sel:DWORD dst_unused:UNUSED_PAD src0_sel:DWORD src1_sel:WORD_1
	v_or_b32_sdwa v42, v11, v9 dst_sel:DWORD dst_unused:UNUSED_PAD src0_sel:WORD_1 src1_sel:DWORD
	v_mul_f32_e32 v3, 0x42000000, v14
	v_mul_f32_e32 v2, 0x42000000, v2
	v_mul_f32_e32 v7, 0x42000000, v56
	v_mul_f32_e32 v9, 0x42000000, v9
	v_med3_f32 v3, v3, s12, v54
	v_med3_f32 v2, v2, s12, v54
	v_med3_f32 v7, v7, s12, v54
	v_med3_f32 v9, v9, s12, v54
	v_cvt_pk_fp8_f32 v44, v3, v2
	v_cvt_pk_fp8_f32 v45, v7, v9
	v_mul_f32_e32 v6, 0x42000000, v15
	v_mul_f32_e32 v5, 0x42000000, v5
	v_mul_f32_e32 v11, 0x42000000, v57
	v_mul_f32_e32 v10, 0x42000000, v10
	v_med3_f32 v6, v6, s12, v54
	v_med3_f32 v5, v5, s12, v54
	v_med3_f32 v11, v11, s12, v54
	v_med3_f32 v10, v10, s12, v54
	v_cvt_pk_fp8_f32 v44, v6, v5 op_sel:[0,0,1]
	v_cvt_pk_fp8_f32 v45, v11, v10 op_sel:[0,0,1]
	global_store_dwordx4 v[34:35], v[40:43], off offset:2048
	v_mov_b32_e32 v9, v39
	v_mov_b32_e32 v5, v38
	global_store_dwordx2 v[36:37], v[44:45], off offset:1024
	s_nop 1
	v_mov_b32_e32 v40, v168
	v_mov_b32_e32 v41, v169
	v_mov_b32_e32 v42, v170
	v_mov_b32_e32 v43, v171
	v_mov_b32_e32 v56, v172
	v_mov_b32_e32 v57, v173
	v_mov_b32_e32 v58, v174
	v_mov_b32_e32 v59, v175
	v_mov_b32_e32 v60, v176
	v_mov_b32_e32 v61, v177
	v_mov_b32_e32 v62, v178
	v_mov_b32_e32 v63, v179
	v_mov_b32_e32 v64, v180
	v_mov_b32_e32 v65, v181
	v_mov_b32_e32 v66, v182
	v_mov_b32_e32 v67, v183
	v_pk_mul_f32 v[2:3], v[16:17], v[46:47] op_sel_hi:[1,0]
	v_pk_mul_f32 v[10:11], v[12:13], v[46:47] op_sel_hi:[1,0]
	v_pk_mul_f32 v[8:9], v[8:9], v[46:47] op_sel_hi:[1,0]
	v_pk_mul_f32 v[4:5], v[4:5], v[46:47] op_sel_hi:[1,0]
	v_mov_b32_e32 v6, 0
	v_mov_b32_e32 v7, 0
	v_mov_b32_e32 v12, v41
	v_mov_b32_e32 v13, v42
	v_mov_b32_e32 v14, v57
	v_mov_b32_e32 v15, v58
	v_mov_b32_e32 v41, v43
	v_mov_b32_e32 v57, v59
	v_mov_b32_e32 v16, v61
	v_mov_b32_e32 v17, v62
	v_mov_b32_e32 v38, v65
	v_mov_b32_e32 v39, v66
	v_mov_b32_e32 v61, v63
	v_mov_b32_e32 v65, v67
	v_pk_fma_f32 v[2:3], v[12:13], v[2:3], v[14:15]
	v_pk_fma_f32 v[10:11], v[40:41], v[10:11], v[56:57]
	v_pk_fma_f32 v[8:9], v[16:17], v[8:9], v[38:39]
	v_pk_fma_f32 v[4:5], v[60:61], v[4:5], v[64:65]
	v_and_b32_sdwa v12, v3, v55 dst_sel:DWORD dst_unused:UNUSED_PAD src0_sel:WORD_1 src1_sel:DWORD
	v_and_b32_sdwa v13, v2, v55 dst_sel:DWORD dst_unused:UNUSED_PAD src0_sel:WORD_1 src1_sel:DWORD
	v_and_b32_sdwa v15, v10, v55 dst_sel:DWORD dst_unused:UNUSED_PAD src0_sel:WORD_1 src1_sel:DWORD
	v_and_b32_sdwa v17, v8, v55 dst_sel:DWORD dst_unused:UNUSED_PAD src0_sel:WORD_1 src1_sel:DWORD
	v_and_b32_sdwa v39, v4, v55 dst_sel:DWORD dst_unused:UNUSED_PAD src0_sel:WORD_1 src1_sel:DWORD
	v_and_b32_sdwa v14, v11, v55 dst_sel:DWORD dst_unused:UNUSED_PAD src0_sel:WORD_1 src1_sel:DWORD
	v_add3_u32 v3, v3, v12, s5
	v_add3_u32 v2, v2, v13, s5
	v_add3_u32 v10, v10, v15, s5
	v_add3_u32 v8, v8, v17, s5
	v_add3_u32 v4, v4, v39, s5
	v_add3_u32 v11, v11, v14, s5
	v_and_b32_e32 v12, 0xffff0000, v2
	v_and_b32_e32 v8, 0xffff0000, v8
	v_and_b32_e32 v13, 0xffff0000, v10
	v_and_b32_e32 v14, 0xffff0000, v3
	v_and_b32_e32 v15, 0xffff0000, v4
	v_or_b32_sdwa v2, v10, v12 dst_sel:DWORD dst_unused:UNUSED_PAD src0_sel:WORD_1 src1_sel:DWORD
	v_mul_f32_e32 v10, 0x42000000, v13
	v_mul_f32_e32 v12, 0x42000000, v12
	v_mul_f32_e32 v13, 0x42000000, v14
	v_mul_f32_e32 v14, 0x42000000, v15
	v_mul_f32_e32 v15, 0x42000000, v8
	v_and_b32_sdwa v16, v9, v55 dst_sel:DWORD dst_unused:UNUSED_PAD src0_sel:WORD_1 src1_sel:DWORD
	v_and_b32_sdwa v38, v5, v55 dst_sel:DWORD dst_unused:UNUSED_PAD src0_sel:WORD_1 src1_sel:DWORD
	v_med3_f32 v10, v10, s12, v54
	v_med3_f32 v12, v12, s12, v54
	v_med3_f32 v14, v14, s12, v54
	v_med3_f32 v15, v15, s12, v54
	v_add3_u32 v9, v9, v16, s5
	v_add3_u32 v5, v5, v38, s5
	v_cvt_pk_fp8_f32 v6, v10, v12
	v_cvt_pk_fp8_f32 v7, v14, v15
	v_and_b32_e32 v11, 0xffff0000, v11
	v_and_b32_e32 v5, 0xffff0000, v5
	v_and_b32_e32 v16, 0xffff0000, v9
	v_or_b32_sdwa v3, v11, v3 dst_sel:DWORD dst_unused:UNUSED_PAD src0_sel:DWORD src1_sel:WORD_1
	v_mul_f32_e32 v11, 0x42000000, v11
	v_mul_f32_e32 v16, 0x42000000, v16
	v_mul_f32_e32 v17, 0x42000000, v5
	v_med3_f32 v13, v13, s12, v54
	v_med3_f32 v11, v11, s12, v54
	v_med3_f32 v10, v16, s12, v54
	v_med3_f32 v12, v17, s12, v54
	v_cvt_pk_fp8_f32 v6, v13, v11 op_sel:[0,0,1]
	v_cvt_pk_fp8_f32 v7, v10, v12 op_sel:[0,0,1]
	v_or_b32_sdwa v5, v5, v9 dst_sel:DWORD dst_unused:UNUSED_PAD src0_sel:DWORD src1_sel:WORD_1
	v_or_b32_sdwa v4, v4, v8 dst_sel:DWORD dst_unused:UNUSED_PAD src0_sel:WORD_1 src1_sel:DWORD
	global_store_dwordx4 v[34:35], v[2:5], off offset:3072
	global_store_dwordx2 v[36:37], v[6:7], off offset:1536
	s_waitcnt vmcnt(8)
	s_cbranch_scc1 .LBB0_596
